# up epilogue ACT stores in saddr form (SGPR base + 32-bit VGPR offset) to halve address traffic per store; on v91
# speedup vs baseline: 1.0060x; 1.0060x over previous
; #define PG8_GAS __attribute__((address_space(1)))
; __device__ __forceinline__ unsigned cvtpk(float lo, float hi) { f32x2 v = {lo, hi}; bf16x2_t b = __builtin_convertvector(v, bf16x2_t); return __builtin_bit_cast(unsigned, b); }
; __device__ __forceinline__ float silu_mul(float g, float u) { return g * u * __builtin_amdgcn_rcpf(1.0f + __builtin_amdgcn_exp2f(-1.4426950408889634f * g)); }
;     __device__ __forceinline__ void operator()(const f32x4 (&acc)[2][2][4][2], const Unit& u, int wr, int wc, int fr, int fq) const {
;         const int row0 = u.pm * BM + wr * 64 + fr, col0 = u.pn * HALF + wc * 32 + 8 * fq;
; #pragma unroll
;         for (int ai = 0; ai < 2; ++ai)
; #pragma unroll
;             for (int m = 0; m < 4; ++m) {
;                 bf16_t* p = O + (size_t)(row0 + ai * HALF + m * 16) * ldc + col0;
;                 const f32x4 g0 = acc[ai][0][m][0], g1 = acc[ai][0][m][1], u0 = acc[ai][1][m][0], u1 = acc[ai][1][m][1];
;                 u32x4 w;
;                 w.x = cvtpk(silu_mul(g0[0], u0[0]), silu_mul(g0[1], u0[1])); w.y = cvtpk(silu_mul(g0[2], u0[2]), silu_mul(g0[3], u0[3]));
;                 w.z = cvtpk(silu_mul(g1[0], u1[0]), silu_mul(g1[1], u1[1])); w.w = cvtpk(silu_mul(g1[2], u1[2]), silu_mul(g1[3], u1[3]));
;                 __builtin_nontemporal_store(w, (PG8_GAS u32x4*)p);
;             }
.LBB0_191:
	s_mov_b32 s54, 0xbfb8aa3b
	s_mov_b32 s55, 0xbfb8aa3b
	v_lshl_add_u32 v149, s33, 8, v5
	v_lshl_or_b32 v144, s31, 7, v147
	v_mul_lo_u32 v150, v149, s93
	v_lshl_add_u32 v150, v144, 1, v150
	v_pk_mul_f32 v[152:153], v[126:127], s[54:55]
	v_pk_mul_f32 v[154:155], v[128:129], s[54:55]
	v_exp_f32_e32 v152, v152
	v_exp_f32_e32 v153, v153
	v_exp_f32_e32 v154, v154
	v_exp_f32_e32 v155, v155
	v_pk_mul_f32 v[126:127], v[126:127], v[130:131]
	v_pk_mul_f32 v[128:129], v[128:129], v[132:133]
	v_pk_add_f32 v[152:153], v[152:153], 1.0 op_sel_hi:[1,0]
	v_pk_add_f32 v[154:155], v[154:155], 1.0 op_sel_hi:[1,0]
	v_rcp_f32_e32 v152, v152
	v_rcp_f32_e32 v153, v153
	v_rcp_f32_e32 v154, v154
	v_rcp_f32_e32 v155, v155
	v_pk_mul_f32 v[126:127], v[152:153], v[126:127]
	v_pk_mul_f32 v[128:129], v[154:155], v[128:129]
	v_cvt_pk_bf16_f32 v126, v126, v127
	v_cvt_pk_bf16_f32 v127, v128, v129
	v_pk_mul_f32 v[152:153], v[118:119], s[54:55]
	v_pk_mul_f32 v[154:155], v[120:121], s[54:55]
	v_exp_f32_e32 v152, v152
	v_exp_f32_e32 v153, v153
	v_exp_f32_e32 v154, v154
	v_exp_f32_e32 v155, v155
	v_pk_mul_f32 v[118:119], v[118:119], v[122:123]
	v_pk_mul_f32 v[120:121], v[120:121], v[124:125]
	v_pk_add_f32 v[152:153], v[152:153], 1.0 op_sel_hi:[1,0]
	v_pk_add_f32 v[154:155], v[154:155], 1.0 op_sel_hi:[1,0]
	v_rcp_f32_e32 v152, v152
	v_rcp_f32_e32 v153, v153
	v_rcp_f32_e32 v154, v154
	v_rcp_f32_e32 v155, v155
	v_pk_mul_f32 v[118:119], v[152:153], v[118:119]
	v_pk_mul_f32 v[120:121], v[154:155], v[120:121]
	v_cvt_pk_bf16_f32 v128, v118, v119
	v_cvt_pk_bf16_f32 v129, v120, v121
	global_store_dwordx4 v150, v[126:129], s[6:7] nt
	v_add_u32_e32 v150, 0x16000, v150
	s_cmp_eq_u64 s[72:73], 0
	s_cbranch_scc1 .Lup_epi_nobar
	s_barrier
.Lup_epi_nobar:
	v_pk_mul_f32 v[152:153], v[110:111], s[54:55]
	v_pk_mul_f32 v[154:155], v[112:113], s[54:55]
	v_exp_f32_e32 v152, v152
	v_exp_f32_e32 v153, v153
	v_exp_f32_e32 v154, v154
	v_exp_f32_e32 v155, v155
	v_pk_mul_f32 v[110:111], v[110:111], v[114:115]
	v_pk_mul_f32 v[112:113], v[112:113], v[116:117]
	v_pk_add_f32 v[152:153], v[152:153], 1.0 op_sel_hi:[1,0]
	v_pk_add_f32 v[154:155], v[154:155], 1.0 op_sel_hi:[1,0]
	v_rcp_f32_e32 v152, v152
	v_rcp_f32_e32 v153, v153
	v_rcp_f32_e32 v154, v154
	v_rcp_f32_e32 v155, v155
	v_pk_mul_f32 v[110:111], v[152:153], v[110:111]
	v_pk_mul_f32 v[112:113], v[154:155], v[112:113]
	v_cvt_pk_bf16_f32 v110, v110, v111
	v_cvt_pk_bf16_f32 v111, v112, v113
	v_pk_mul_f32 v[152:153], v[102:103], s[54:55]
	v_pk_mul_f32 v[154:155], v[104:105], s[54:55]
	v_exp_f32_e32 v152, v152
	v_exp_f32_e32 v153, v153
	v_exp_f32_e32 v154, v154
	v_exp_f32_e32 v155, v155
	v_pk_mul_f32 v[102:103], v[102:103], v[106:107]
	v_pk_mul_f32 v[104:105], v[104:105], v[108:109]
	v_pk_add_f32 v[152:153], v[152:153], 1.0 op_sel_hi:[1,0]
	v_pk_add_f32 v[154:155], v[154:155], 1.0 op_sel_hi:[1,0]
	v_rcp_f32_e32 v152, v152
	v_rcp_f32_e32 v153, v153
	v_rcp_f32_e32 v154, v154
	v_rcp_f32_e32 v155, v155
	v_pk_mul_f32 v[102:103], v[152:153], v[102:103]
	v_pk_mul_f32 v[104:105], v[154:155], v[104:105]
	v_cvt_pk_bf16_f32 v112, v102, v103
	v_cvt_pk_bf16_f32 v113, v104, v105
	global_store_dwordx4 v150, v[110:113], s[6:7] nt
	v_add_u32_e32 v150, 0x16000, v150
	v_pk_mul_f32 v[152:153], v[94:95], s[54:55]
	v_pk_mul_f32 v[154:155], v[96:97], s[54:55]
	v_exp_f32_e32 v152, v152
	v_exp_f32_e32 v153, v153
	v_exp_f32_e32 v154, v154
	v_exp_f32_e32 v155, v155
	v_pk_mul_f32 v[94:95], v[94:95], v[98:99]
	v_pk_mul_f32 v[96:97], v[96:97], v[100:101]
	v_pk_add_f32 v[152:153], v[152:153], 1.0 op_sel_hi:[1,0]
	v_pk_add_f32 v[154:155], v[154:155], 1.0 op_sel_hi:[1,0]
	v_rcp_f32_e32 v152, v152
	v_rcp_f32_e32 v153, v153
	v_rcp_f32_e32 v154, v154
	v_rcp_f32_e32 v155, v155
	v_pk_mul_f32 v[94:95], v[152:153], v[94:95]
	v_pk_mul_f32 v[96:97], v[154:155], v[96:97]
	v_cvt_pk_bf16_f32 v94, v94, v95
	v_cvt_pk_bf16_f32 v95, v96, v97
	v_pk_mul_f32 v[152:153], v[86:87], s[54:55]
	v_pk_mul_f32 v[154:155], v[88:89], s[54:55]
	v_exp_f32_e32 v152, v152
	v_exp_f32_e32 v153, v153
	v_exp_f32_e32 v154, v154
	v_exp_f32_e32 v155, v155
	v_pk_mul_f32 v[86:87], v[86:87], v[90:91]
	v_pk_mul_f32 v[88:89], v[88:89], v[92:93]
	v_pk_add_f32 v[152:153], v[152:153], 1.0 op_sel_hi:[1,0]
	v_pk_add_f32 v[154:155], v[154:155], 1.0 op_sel_hi:[1,0]
	v_rcp_f32_e32 v152, v152
	v_rcp_f32_e32 v153, v153
	v_rcp_f32_e32 v154, v154
	v_rcp_f32_e32 v155, v155
	v_pk_mul_f32 v[86:87], v[152:153], v[86:87]
	v_pk_mul_f32 v[88:89], v[154:155], v[88:89]
	v_cvt_pk_bf16_f32 v96, v86, v87
	v_cvt_pk_bf16_f32 v97, v88, v89
	global_store_dwordx4 v150, v[94:97], s[6:7] nt
	v_add_u32_e32 v150, 0x16000, v150
	v_pk_mul_f32 v[152:153], v[78:79], s[54:55]
	v_pk_mul_f32 v[154:155], v[80:81], s[54:55]
	v_exp_f32_e32 v152, v152
	v_exp_f32_e32 v153, v153
	v_exp_f32_e32 v154, v154
	v_exp_f32_e32 v155, v155
	v_pk_mul_f32 v[78:79], v[78:79], v[82:83]
	v_pk_mul_f32 v[80:81], v[80:81], v[84:85]
	v_pk_add_f32 v[152:153], v[152:153], 1.0 op_sel_hi:[1,0]
	v_pk_add_f32 v[154:155], v[154:155], 1.0 op_sel_hi:[1,0]
	v_rcp_f32_e32 v152, v152
	v_rcp_f32_e32 v153, v153
	v_rcp_f32_e32 v154, v154
	v_rcp_f32_e32 v155, v155
	v_pk_mul_f32 v[78:79], v[152:153], v[78:79]
	v_pk_mul_f32 v[80:81], v[154:155], v[80:81]
	v_cvt_pk_bf16_f32 v78, v78, v79
	v_cvt_pk_bf16_f32 v79, v80, v81
	v_pk_mul_f32 v[152:153], v[70:71], s[54:55]
	v_pk_mul_f32 v[154:155], v[72:73], s[54:55]
	v_exp_f32_e32 v152, v152
	v_exp_f32_e32 v153, v153
	v_exp_f32_e32 v154, v154
	v_exp_f32_e32 v155, v155
	v_pk_mul_f32 v[70:71], v[70:71], v[74:75]
	v_pk_mul_f32 v[72:73], v[72:73], v[76:77]
	v_pk_add_f32 v[152:153], v[152:153], 1.0 op_sel_hi:[1,0]
	v_pk_add_f32 v[154:155], v[154:155], 1.0 op_sel_hi:[1,0]
; #define PG8_GAS __attribute__((address_space(1)))
; __device__ __forceinline__ unsigned cvtpk(float lo, float hi) { f32x2 v = {lo, hi}; bf16x2_t b = __builtin_convertvector(v, bf16x2_t); return __builtin_bit_cast(unsigned, b); }
; __device__ __forceinline__ float silu_mul(float g, float u) { return g * u * __builtin_amdgcn_rcpf(1.0f + __builtin_amdgcn_exp2f(-1.4426950408889634f * g)); }
; #define PG8_BAR __builtin_amdgcn_s_barrier()
;     __device__ __forceinline__ void operator()(const f32x4 (&acc)[2][2][4][2], const Unit& u, int wr, int wc, int fr, int fq) const {
;         const int row0 = u.pm * BM + wr * 64 + fr, col0 = u.pn * HALF + wc * 32 + 8 * fq;
; #pragma unroll
;         for (int ai = 0; ai < 2; ++ai)
; #pragma unroll
;             for (int m = 0; m < 4; ++m) {
;                 bf16_t* p = O + (size_t)(row0 + ai * HALF + m * 16) * ldc + col0;
;                 const f32x4 g0 = acc[ai][0][m][0], g1 = acc[ai][0][m][1], u0 = acc[ai][1][m][0], u1 = acc[ai][1][m][1];
;                 u32x4 w;
;                 w.x = cvtpk(silu_mul(g0[0], u0[0]), silu_mul(g0[1], u0[1])); w.y = cvtpk(silu_mul(g0[2], u0[2]), silu_mul(g0[3], u0[3]));
;                 w.z = cvtpk(silu_mul(g1[0], u1[0]), silu_mul(g1[1], u1[1])); w.w = cvtpk(silu_mul(g1[2], u1[2]), silu_mul(g1[3], u1[3]));
;                 __builtin_nontemporal_store(w, (PG8_GAS u32x4*)p);
;             }
; template <class Epi, class Sched, bool ALIGN_EPI = false, bool SP2 = false>
; __device__ __forceinline__ void gemm_phase(PG8_LAS unsigned char* lds, const Gemm g, const Sched& S, const Epi& E, const int tid) {
;     ...
;         if constexpr (ALIGN_EPI) { if (wr == 0) PG8_BAR; }
;         if constexpr (!Epi::AFTER_DRAIN) { E(acc, cur, wr, wc, fr, fq); S.done(cur); }
;         if (!has_next) break;
; #pragma unroll
;         for (int a = 0; a < 2; ++a)
; #pragma unroll
;             for (int b = 0; b < 2; ++b)
; #pragma unroll
;                 for (int m = 0; m < 4; ++m)
; #pragma unroll
;                     for (int n = 0; n < 2; ++n) acc[a][b][m][n] = (f32x4){0.f, 0.f, 0.f, 0.f};
;         cur = nxt; cA = nA; cB = nB; ++ui;
;         if constexpr (ALIGN_EPI) { if (wr == 1) PG8_BAR; }
;     }
	v_rcp_f32_e32 v152, v152
	v_rcp_f32_e32 v153, v153
	v_rcp_f32_e32 v154, v154
	v_rcp_f32_e32 v155, v155
	v_pk_mul_f32 v[70:71], v[152:153], v[70:71]
	v_pk_mul_f32 v[72:73], v[154:155], v[72:73]
	v_cvt_pk_bf16_f32 v80, v70, v71
	v_cvt_pk_bf16_f32 v81, v72, v73
	global_store_dwordx4 v150, v[78:81], s[6:7] nt
	v_add_u32_e32 v150, 0x6e000, v150
	v_pk_mul_f32 v[152:153], v[62:63], s[54:55]
	v_pk_mul_f32 v[154:155], v[64:65], s[54:55]
	v_exp_f32_e32 v152, v152
	v_exp_f32_e32 v153, v153
	v_exp_f32_e32 v154, v154
	v_exp_f32_e32 v155, v155
	v_pk_mul_f32 v[62:63], v[62:63], v[66:67]
	v_pk_mul_f32 v[64:65], v[64:65], v[68:69]
	v_pk_add_f32 v[152:153], v[152:153], 1.0 op_sel_hi:[1,0]
	v_pk_add_f32 v[154:155], v[154:155], 1.0 op_sel_hi:[1,0]
	v_rcp_f32_e32 v152, v152
	v_rcp_f32_e32 v153, v153
	v_rcp_f32_e32 v154, v154
	v_rcp_f32_e32 v155, v155
	v_pk_mul_f32 v[62:63], v[152:153], v[62:63]
	v_pk_mul_f32 v[64:65], v[154:155], v[64:65]
	v_cvt_pk_bf16_f32 v62, v62, v63
	v_cvt_pk_bf16_f32 v63, v64, v65
	v_pk_mul_f32 v[152:153], v[54:55], s[54:55]
	v_pk_mul_f32 v[154:155], v[56:57], s[54:55]
	v_exp_f32_e32 v152, v152
	v_exp_f32_e32 v153, v153
	v_exp_f32_e32 v154, v154
	v_exp_f32_e32 v155, v155
	v_pk_mul_f32 v[54:55], v[54:55], v[58:59]
	v_pk_mul_f32 v[56:57], v[56:57], v[60:61]
	v_pk_add_f32 v[152:153], v[152:153], 1.0 op_sel_hi:[1,0]
	v_pk_add_f32 v[154:155], v[154:155], 1.0 op_sel_hi:[1,0]
	v_rcp_f32_e32 v152, v152
	v_rcp_f32_e32 v153, v153
	v_rcp_f32_e32 v154, v154
	v_rcp_f32_e32 v155, v155
	v_pk_mul_f32 v[54:55], v[152:153], v[54:55]
	v_pk_mul_f32 v[56:57], v[154:155], v[56:57]
	v_cvt_pk_bf16_f32 v64, v54, v55
	v_cvt_pk_bf16_f32 v65, v56, v57
	global_store_dwordx4 v150, v[62:65], s[6:7] nt
	v_add_u32_e32 v150, 0x16000, v150
	v_pk_mul_f32 v[152:153], v[46:47], s[54:55]
	v_pk_mul_f32 v[154:155], v[48:49], s[54:55]
	v_exp_f32_e32 v152, v152
	v_exp_f32_e32 v153, v153
	v_exp_f32_e32 v154, v154
	v_exp_f32_e32 v155, v155
	v_pk_mul_f32 v[46:47], v[46:47], v[50:51]
	v_pk_mul_f32 v[48:49], v[48:49], v[52:53]
	v_pk_add_f32 v[152:153], v[152:153], 1.0 op_sel_hi:[1,0]
	v_pk_add_f32 v[154:155], v[154:155], 1.0 op_sel_hi:[1,0]
	v_rcp_f32_e32 v152, v152
	v_rcp_f32_e32 v153, v153
	v_rcp_f32_e32 v154, v154
	v_rcp_f32_e32 v155, v155
	v_pk_mul_f32 v[46:47], v[152:153], v[46:47]
	v_pk_mul_f32 v[48:49], v[154:155], v[48:49]
	v_cvt_pk_bf16_f32 v46, v46, v47
	v_cvt_pk_bf16_f32 v47, v48, v49
	v_pk_mul_f32 v[152:153], v[38:39], s[54:55]
	v_pk_mul_f32 v[154:155], v[40:41], s[54:55]
	v_exp_f32_e32 v152, v152
	v_exp_f32_e32 v153, v153
	v_exp_f32_e32 v154, v154
	v_exp_f32_e32 v155, v155
	v_pk_mul_f32 v[38:39], v[38:39], v[42:43]
	v_pk_mul_f32 v[40:41], v[40:41], v[44:45]
	v_pk_add_f32 v[152:153], v[152:153], 1.0 op_sel_hi:[1,0]
	v_pk_add_f32 v[154:155], v[154:155], 1.0 op_sel_hi:[1,0]
	v_rcp_f32_e32 v152, v152
	v_rcp_f32_e32 v153, v153
	v_rcp_f32_e32 v154, v154
	v_rcp_f32_e32 v155, v155
	v_pk_mul_f32 v[38:39], v[152:153], v[38:39]
	v_pk_mul_f32 v[40:41], v[154:155], v[40:41]
	v_cvt_pk_bf16_f32 v48, v38, v39
	v_cvt_pk_bf16_f32 v49, v40, v41
	global_store_dwordx4 v150, v[46:49], s[6:7] nt
	v_add_u32_e32 v150, 0x16000, v150
	v_pk_mul_f32 v[152:153], v[30:31], s[54:55]
	v_pk_mul_f32 v[154:155], v[32:33], s[54:55]
	v_exp_f32_e32 v152, v152
	v_exp_f32_e32 v153, v153
	v_exp_f32_e32 v154, v154
	v_exp_f32_e32 v155, v155
	v_pk_mul_f32 v[30:31], v[30:31], v[34:35]
	v_pk_mul_f32 v[32:33], v[32:33], v[36:37]
	v_pk_add_f32 v[152:153], v[152:153], 1.0 op_sel_hi:[1,0]
	v_pk_add_f32 v[154:155], v[154:155], 1.0 op_sel_hi:[1,0]
	v_rcp_f32_e32 v152, v152
	v_rcp_f32_e32 v153, v153
	v_rcp_f32_e32 v154, v154
	v_rcp_f32_e32 v155, v155
	v_pk_mul_f32 v[30:31], v[152:153], v[30:31]
	v_pk_mul_f32 v[32:33], v[154:155], v[32:33]
	v_cvt_pk_bf16_f32 v30, v30, v31
	v_cvt_pk_bf16_f32 v31, v32, v33
	v_pk_mul_f32 v[152:153], v[22:23], s[54:55]
	v_pk_mul_f32 v[154:155], v[24:25], s[54:55]
	v_exp_f32_e32 v152, v152
	v_exp_f32_e32 v153, v153
	v_exp_f32_e32 v154, v154
	v_exp_f32_e32 v155, v155
	v_pk_mul_f32 v[22:23], v[22:23], v[26:27]
	v_pk_mul_f32 v[24:25], v[24:25], v[28:29]
	v_pk_add_f32 v[152:153], v[152:153], 1.0 op_sel_hi:[1,0]
	v_pk_add_f32 v[154:155], v[154:155], 1.0 op_sel_hi:[1,0]
	v_rcp_f32_e32 v152, v152
	v_rcp_f32_e32 v153, v153
	v_rcp_f32_e32 v154, v154
	v_rcp_f32_e32 v155, v155
	v_pk_mul_f32 v[22:23], v[152:153], v[22:23]
	v_pk_mul_f32 v[24:25], v[154:155], v[24:25]
	v_cvt_pk_bf16_f32 v32, v22, v23
	v_cvt_pk_bf16_f32 v33, v24, v25
	global_store_dwordx4 v150, v[30:33], s[6:7] nt
	v_add_u32_e32 v150, 0x16000, v150
	v_pk_mul_f32 v[152:153], v[14:15], s[54:55]
	v_pk_mul_f32 v[154:155], v[16:17], s[54:55]
	v_exp_f32_e32 v152, v152
	v_exp_f32_e32 v153, v153
	v_exp_f32_e32 v154, v154
	v_exp_f32_e32 v155, v155
	v_pk_mul_f32 v[14:15], v[14:15], v[18:19]
	v_pk_mul_f32 v[16:17], v[16:17], v[20:21]
	v_pk_add_f32 v[152:153], v[152:153], 1.0 op_sel_hi:[1,0]
	v_pk_add_f32 v[154:155], v[154:155], 1.0 op_sel_hi:[1,0]
	v_rcp_f32_e32 v152, v152
	v_rcp_f32_e32 v153, v153
	v_rcp_f32_e32 v154, v154
	v_rcp_f32_e32 v155, v155
	v_pk_mul_f32 v[14:15], v[152:153], v[14:15]
	v_pk_mul_f32 v[16:17], v[154:155], v[16:17]
	v_cvt_pk_bf16_f32 v14, v14, v15
	v_cvt_pk_bf16_f32 v15, v16, v17
	v_pk_mul_f32 v[152:153], v[10:11], s[54:55]
	v_pk_mul_f32 v[154:155], v[12:13], s[54:55]
	v_exp_f32_e32 v152, v152
	v_exp_f32_e32 v153, v153
	v_exp_f32_e32 v154, v154
	v_exp_f32_e32 v155, v155
	v_pk_mul_f32 v[10:11], v[10:11], v[6:7]
	v_pk_mul_f32 v[12:13], v[12:13], v[8:9]
	v_pk_add_f32 v[152:153], v[152:153], 1.0 op_sel_hi:[1,0]
	v_pk_add_f32 v[154:155], v[154:155], 1.0 op_sel_hi:[1,0]
	v_rcp_f32_e32 v152, v152
	v_rcp_f32_e32 v153, v153
	v_rcp_f32_e32 v154, v154
	v_rcp_f32_e32 v155, v155
	v_pk_mul_f32 v[10:11], v[152:153], v[10:11]
	v_pk_mul_f32 v[12:13], v[154:155], v[12:13]
	v_cvt_pk_bf16_f32 v16, v10, v11
	v_cvt_pk_bf16_f32 v17, v12, v13
	global_store_dwordx4 v150, v[14:17], s[6:7] nt
	s_mov_b64 s[82:83], -1
	s_andn2_b64 vcc, exec, s[4:5]
	s_cbranch_vccnz .LBB0_184
	s_andn2_b64 vcc, exec, s[70:71]
	s_cbranch_vccnz .LBB0_183
	s_barrier
	s_branch .LBB0_183
